# C + all eight GEMM K-loop heads padded to byte phase 32 mod 64 (code placement)
# baseline (speedup 1.0000x reference)
;     __device__ bool next(int i, Unit& u) const { if (i != 0) return false; return so.next(round, u); }
;     __device__ __forceinline__ bool next(int i, Unit& u) const { if (i > 0 || !on) return false; u.pm = pm; u.pn = 0; return true; }
; template <class Epi, class Sched, bool ALIGN_EPI = false, bool SP2 = false, bool MIDHOOK = false>
; __device__ __forceinline__ void gemm_phase(PG8_LAS unsigned char* lds, const Gemm g, const Sched& S, const Epi& E) {
;     ...
;         const bool has_next = S.next(ui + 1, nxt);
;         const char* nA = has_next ? (const char*)g.A + (size_t)nxt.pm * tstep : cA; const char* nB = has_next ? (const char*)g.Bt + (size_t)nxt.pn * tstep : cB;
;     ...
; #pragma unroll
;         for (int a = 0; a < 2; ++a)
; #pragma unroll
;             for (int b = 0; b < 2; ++b)
; #pragma unroll
;                 for (int m = 0; m < 4; ++m)
; #pragma unroll
;                     for (int n = 0; n < 2; ++n) acc[a][b][m][n] = (f32x4){0.f, 0.f, 0.f, 0.f};
;         cur = nxt; cA = nA; cB = nB; ++ui;
.LBB0_190:
	s_ashr_i32 s41, s40, 31
	s_lshl_b64 s[42:43], s[40:41], 19
	v_readlane_b32 s12, v243, 48
	v_readlane_b32 s13, v243, 49
	s_add_u32 s42, s12, s42
	s_addc_u32 s43, s13, s43
	s_and_b64 s[44:45], s[0:1], exec
	s_cselect_b32 s5, s43, s7
	s_cselect_b32 s41, s42, s6
	s_ashr_i32 s39, s38, 31
	s_lshl_b64 s[44:45], s[38:39], 19
	s_add_u32 s44, s24, s44
	s_addc_u32 s45, s25, s45
	s_and_b64 s[48:49], s[0:1], exec
	s_cselect_b32 s39, s45, s9
	s_cselect_b32 s62, s44, s8
	s_add_u32 s6, s6, 0x40080
	s_addc_u32 s7, s7, 0
	s_add_u32 s63, s8, 0x100
	v_mov_b32_e32 v0, 0
	s_addc_u32 s64, s9, 0
	s_mov_b32 s65, -2
	v_mov_b32_e32 v1, v0
	v_mov_b32_e32 v2, v0
	v_mov_b32_e32 v3, v0
	v_mov_b32_e32 v8, v0
	v_mov_b32_e32 v9, v0
	v_mov_b32_e32 v10, v0
	v_mov_b32_e32 v11, v0
	v_mov_b32_e32 v16, v0
	v_mov_b32_e32 v17, v0
	v_mov_b32_e32 v18, v0
	v_mov_b32_e32 v19, v0
	v_mov_b32_e32 v24, v0
	v_mov_b32_e32 v25, v0
	v_mov_b32_e32 v26, v0
	v_mov_b32_e32 v27, v0
	v_mov_b32_e32 v32, v0
	v_mov_b32_e32 v33, v0
	v_mov_b32_e32 v34, v0
	v_mov_b32_e32 v35, v0
	v_mov_b32_e32 v40, v0
	v_mov_b32_e32 v41, v0
	v_mov_b32_e32 v42, v0
	v_mov_b32_e32 v43, v0
	v_mov_b32_e32 v48, v0
	v_mov_b32_e32 v49, v0
	v_mov_b32_e32 v50, v0
	v_mov_b32_e32 v51, v0
	v_mov_b32_e32 v56, v0
	v_mov_b32_e32 v57, v0
	v_mov_b32_e32 v58, v0
	v_mov_b32_e32 v59, v0
	v_mov_b32_e32 v4, v0
	v_mov_b32_e32 v5, v0
	v_mov_b32_e32 v6, v0
	v_mov_b32_e32 v7, v0
	v_mov_b32_e32 v12, v0
	v_mov_b32_e32 v13, v0
	v_mov_b32_e32 v14, v0
	v_mov_b32_e32 v15, v0
	v_mov_b32_e32 v20, v0
	v_mov_b32_e32 v21, v0
	v_mov_b32_e32 v22, v0
	v_mov_b32_e32 v23, v0
	v_mov_b32_e32 v28, v0
	v_mov_b32_e32 v29, v0
	v_mov_b32_e32 v30, v0
	v_mov_b32_e32 v31, v0
	v_mov_b32_e32 v36, v0
	v_mov_b32_e32 v37, v0
	v_mov_b32_e32 v38, v0
	v_mov_b32_e32 v39, v0
	v_mov_b32_e32 v44, v0
	v_mov_b32_e32 v45, v0
	v_mov_b32_e32 v46, v0
	v_mov_b32_e32 v47, v0
	v_mov_b32_e32 v52, v0
	v_mov_b32_e32 v53, v0
	v_mov_b32_e32 v54, v0
	v_mov_b32_e32 v55, v0
	v_mov_b32_e32 v60, v0
	v_mov_b32_e32 v61, v0
	v_mov_b32_e32 v62, v0
	v_mov_b32_e32 v63, v0
	v_mov_b32_e32 v64, v0
	v_mov_b32_e32 v65, v0
	v_mov_b32_e32 v66, v0
	v_mov_b32_e32 v67, v0
	v_mov_b32_e32 v72, v0
	v_mov_b32_e32 v73, v0
	v_mov_b32_e32 v74, v0
	v_mov_b32_e32 v75, v0
	v_mov_b32_e32 v80, v0
	v_mov_b32_e32 v81, v0
	v_mov_b32_e32 v82, v0
	v_mov_b32_e32 v83, v0
	v_mov_b32_e32 v88, v0
	v_mov_b32_e32 v89, v0
	v_mov_b32_e32 v90, v0
	v_mov_b32_e32 v91, v0
	v_mov_b32_e32 v96, v0
	v_mov_b32_e32 v97, v0
	v_mov_b32_e32 v98, v0
	v_mov_b32_e32 v99, v0
	v_mov_b32_e32 v104, v0
	v_mov_b32_e32 v105, v0
	v_mov_b32_e32 v106, v0
	v_mov_b32_e32 v107, v0
	v_mov_b32_e32 v112, v0
	v_mov_b32_e32 v113, v0
	v_mov_b32_e32 v114, v0
	v_mov_b32_e32 v115, v0
	v_mov_b32_e32 v120, v0
	v_mov_b32_e32 v121, v0
	v_mov_b32_e32 v122, v0
	v_mov_b32_e32 v123, v0
	v_mov_b32_e32 v68, v0
	v_mov_b32_e32 v69, v0
	v_mov_b32_e32 v70, v0
	v_mov_b32_e32 v71, v0
	v_mov_b32_e32 v76, v0
	v_mov_b32_e32 v77, v0
	v_mov_b32_e32 v78, v0
	v_mov_b32_e32 v79, v0
	v_mov_b32_e32 v84, v0
	v_mov_b32_e32 v85, v0
	v_mov_b32_e32 v86, v0
	v_mov_b32_e32 v87, v0
	v_mov_b32_e32 v92, v0
	v_mov_b32_e32 v93, v0
	v_mov_b32_e32 v94, v0
	v_mov_b32_e32 v95, v0
	v_mov_b32_e32 v100, v0
	v_mov_b32_e32 v101, v0
	v_mov_b32_e32 v102, v0
	v_mov_b32_e32 v103, v0
	v_mov_b32_e32 v108, v0
	v_mov_b32_e32 v109, v0
	v_mov_b32_e32 v110, v0
	v_mov_b32_e32 v111, v0
	v_mov_b32_e32 v116, v0
	v_mov_b32_e32 v117, v0
	v_mov_b32_e32 v118, v0
	v_mov_b32_e32 v119, v0
	v_mov_b32_e32 v124, v0
	v_mov_b32_e32 v125, v0
	v_mov_b32_e32 v126, v0
	v_mov_b32_e32 v127, v0
	s_nop 0
	s_nop 0
	s_nop 0
	s_nop 0
	s_nop 0
	s_nop 0
	s_nop 0
	s_nop 0
	s_nop 0
	s_nop 0
	s_nop 0
	s_nop 0
	s_nop 0
	s_nop 0
